# GEMM tile heads: 128 accumulators zeroed with 64 v_mov_b64 instead of 128 v_mov_b32 (all 6 GEMM instances)
# speedup vs baseline: 1.0119x; 1.0053x over previous
.LBB0_56:
	s_ashr_i32 s37, s36, 31
	v_cmp_lt_i64_e32 vcc, s[40:41], v[150:151]
	s_lshl_b64 s[40:41], s[36:37], 19
	s_add_u32 s40, s52, s40
	s_addc_u32 s41, s53, s41
	s_and_b64 s[44:45], vcc, exec
	s_cselect_b32 s37, s41, s1
	s_cselect_b32 s60, s40, s0
	s_ashr_i32 s35, s34, 31
	s_lshl_b64 s[44:45], s[34:35], 19
	s_add_u32 s44, s19, s44
	s_addc_u32 s45, s24, s45
	s_and_b64 s[48:49], vcc, exec
	s_cselect_b32 s35, s45, s23
	s_cselect_b32 s61, s44, s22
	s_add_u32 s0, s0, 0x40080
	s_addc_u32 s1, s1, 0
	s_add_u32 s62, s22, 0x100
	s_addc_u32 s63, s23, 0
	s_mov_b32 s64, -2
	v_mov_b64_e32 v[2:3], 0
	v_mov_b64_e32 v[4:5], 0
	v_mov_b64_e32 v[6:7], 0
	v_mov_b64_e32 v[8:9], 0
	v_mov_b64_e32 v[10:11], 0
	v_mov_b64_e32 v[12:13], 0
	v_mov_b64_e32 v[14:15], 0
	v_mov_b64_e32 v[16:17], 0
	v_mov_b64_e32 v[18:19], 0
	v_mov_b64_e32 v[20:21], 0
	v_mov_b64_e32 v[22:23], 0
	v_mov_b64_e32 v[24:25], 0
	v_mov_b64_e32 v[26:27], 0
	v_mov_b64_e32 v[28:29], 0
	v_mov_b64_e32 v[30:31], 0
	v_mov_b64_e32 v[32:33], 0
	v_mov_b64_e32 v[34:35], 0
	v_mov_b64_e32 v[36:37], 0
	v_mov_b64_e32 v[38:39], 0
	v_mov_b64_e32 v[40:41], 0
	v_mov_b64_e32 v[42:43], 0
	v_mov_b64_e32 v[44:45], 0
	v_mov_b64_e32 v[46:47], 0
	v_mov_b64_e32 v[48:49], 0
	v_mov_b64_e32 v[50:51], 0
	v_mov_b64_e32 v[52:53], 0
	v_mov_b64_e32 v[54:55], 0
	v_mov_b64_e32 v[56:57], 0
	v_mov_b64_e32 v[58:59], 0
	v_mov_b64_e32 v[60:61], 0
	v_mov_b64_e32 v[62:63], 0
	v_mov_b64_e32 v[64:65], 0
	v_mov_b64_e32 v[66:67], 0
	v_mov_b64_e32 v[68:69], 0
	v_mov_b64_e32 v[70:71], 0
	v_mov_b64_e32 v[72:73], 0
	v_mov_b64_e32 v[74:75], 0
	v_mov_b64_e32 v[76:77], 0
	v_mov_b64_e32 v[78:79], 0
	v_mov_b64_e32 v[80:81], 0
	v_mov_b64_e32 v[82:83], 0
	v_mov_b64_e32 v[84:85], 0
	v_mov_b64_e32 v[86:87], 0
	v_mov_b64_e32 v[88:89], 0
	v_mov_b64_e32 v[90:91], 0
	v_mov_b64_e32 v[92:93], 0
	v_mov_b64_e32 v[94:95], 0
	v_mov_b64_e32 v[96:97], 0
	v_mov_b64_e32 v[98:99], 0
	v_mov_b64_e32 v[100:101], 0
	v_mov_b64_e32 v[102:103], 0
	v_mov_b64_e32 v[104:105], 0
	v_mov_b64_e32 v[106:107], 0
	v_mov_b64_e32 v[108:109], 0
	v_mov_b64_e32 v[110:111], 0
	v_mov_b64_e32 v[112:113], 0
	v_mov_b64_e32 v[114:115], 0
	v_mov_b64_e32 v[116:117], 0
	v_mov_b64_e32 v[118:119], 0
	v_mov_b64_e32 v[120:121], 0
	v_mov_b64_e32 v[122:123], 0
	v_mov_b64_e32 v[124:125], 0
	v_mov_b64_e32 v[126:127], 0
	v_mov_b64_e32 v[128:129], 0

.LBB0_94:
	s_ashr_i32 s49, s48, 31
	s_lshl_b64 s[26:27], s[48:49], 19
	s_add_u32 s50, s14, s26
	v_cmp_lt_i64_e32 vcc, s[28:29], v[152:153]
	s_addc_u32 s51, s15, s27
	s_and_b64 s[26:27], vcc, exec
	s_cselect_b32 s25, s51, s9
	s_cselect_b32 s26, s50, s8
	s_ashr_i32 s47, s46, 31
	s_lshl_b64 s[28:29], s[46:47], 19
	s_add_u32 s54, s19, s28
	s_addc_u32 s55, s34, s29
	s_and_b64 s[28:29], vcc, exec
	s_cselect_b32 s27, s55, s23
	s_cselect_b32 s30, s54, s22
	s_add_u32 s8, s8, 0x40080
	s_addc_u32 s9, s9, 0
	s_add_u32 s31, s22, 0x100
	s_addc_u32 s47, s23, 0
	s_mov_b32 s49, -2
	v_mov_b64_e32 v[2:3], 0
	v_mov_b64_e32 v[4:5], 0
	v_mov_b64_e32 v[6:7], 0
	v_mov_b64_e32 v[8:9], 0
	v_mov_b64_e32 v[10:11], 0
	v_mov_b64_e32 v[12:13], 0
	v_mov_b64_e32 v[14:15], 0
	v_mov_b64_e32 v[16:17], 0
	v_mov_b64_e32 v[18:19], 0
	v_mov_b64_e32 v[20:21], 0
	v_mov_b64_e32 v[22:23], 0
	v_mov_b64_e32 v[24:25], 0
	v_mov_b64_e32 v[26:27], 0
	v_mov_b64_e32 v[28:29], 0
	v_mov_b64_e32 v[30:31], 0
	v_mov_b64_e32 v[32:33], 0
	v_mov_b64_e32 v[34:35], 0
	v_mov_b64_e32 v[36:37], 0
	v_mov_b64_e32 v[38:39], 0
	v_mov_b64_e32 v[40:41], 0
	v_mov_b64_e32 v[42:43], 0
	v_mov_b64_e32 v[44:45], 0
	v_mov_b64_e32 v[46:47], 0
	v_mov_b64_e32 v[48:49], 0
	v_mov_b64_e32 v[50:51], 0
	v_mov_b64_e32 v[52:53], 0
	v_mov_b64_e32 v[54:55], 0
	v_mov_b64_e32 v[56:57], 0
	v_mov_b64_e32 v[62:63], 0
	v_mov_b64_e32 v[64:65], 0
	v_mov_b64_e32 v[70:71], 0
	v_mov_b64_e32 v[72:73], 0
	v_mov_b64_e32 v[82:83], 0
	v_mov_b64_e32 v[84:85], 0
	v_mov_b64_e32 v[86:87], 0
	v_mov_b64_e32 v[88:89], 0
	v_mov_b64_e32 v[90:91], 0
	v_mov_b64_e32 v[92:93], 0
	v_mov_b64_e32 v[94:95], 0
	v_mov_b64_e32 v[96:97], 0
	v_mov_b64_e32 v[98:99], 0
	v_mov_b64_e32 v[100:101], 0
	v_mov_b64_e32 v[102:103], 0
	v_mov_b64_e32 v[104:105], 0
	v_mov_b64_e32 v[106:107], 0
	v_mov_b64_e32 v[108:109], 0
	v_mov_b64_e32 v[110:111], 0
	v_mov_b64_e32 v[112:113], 0
	v_mov_b64_e32 v[114:115], 0
	v_mov_b64_e32 v[116:117], 0
	v_mov_b64_e32 v[118:119], 0
	v_mov_b64_e32 v[120:121], 0
	v_mov_b64_e32 v[122:123], 0
	v_mov_b64_e32 v[124:125], 0
	v_mov_b64_e32 v[126:127], 0
	v_mov_b64_e32 v[128:129], 0
	v_mov_b64_e32 v[130:131], 0
	v_mov_b64_e32 v[132:133], 0
	v_mov_b64_e32 v[134:135], 0
	v_mov_b64_e32 v[136:137], 0
	v_mov_b64_e32 v[138:139], 0
	v_mov_b64_e32 v[140:141], 0
	v_mov_b64_e32 v[142:143], 0
	v_mov_b64_e32 v[144:145], 0

.LBB0_259:
	s_ashr_i32 s35, s34, 31
	v_cmp_lt_i64_e32 vcc, s[36:37], v[150:151]
	s_lshl_b64 s[36:37], s[34:35], 19
	s_add_u32 s36, s12, s36
	s_addc_u32 s37, s13, s37
	s_and_b64 s[42:43], vcc, exec
	s_cselect_b32 s35, s37, s1
	s_cselect_b32 s55, s36, s0
	s_ashr_i32 s31, s30, 31
	s_lshl_b64 s[42:43], s[30:31], 19
	s_add_u32 s42, s17, s42
	s_addc_u32 s43, s19, s43
	s_and_b64 s[46:47], vcc, exec
	s_cselect_b32 s31, s43, s23
	s_cselect_b32 s56, s42, s22
	s_add_u32 s0, s0, 0x40080
	s_addc_u32 s1, s1, 0
	s_add_u32 s57, s22, 0x100
	s_addc_u32 s58, s23, 0
	s_mov_b32 s59, -2
	v_mov_b64_e32 v[2:3], 0
	v_mov_b64_e32 v[4:5], 0
	v_mov_b64_e32 v[6:7], 0
	v_mov_b64_e32 v[8:9], 0
	v_mov_b64_e32 v[10:11], 0
	v_mov_b64_e32 v[12:13], 0
	v_mov_b64_e32 v[14:15], 0
	v_mov_b64_e32 v[16:17], 0
	v_mov_b64_e32 v[18:19], 0
	v_mov_b64_e32 v[20:21], 0
	v_mov_b64_e32 v[22:23], 0
	v_mov_b64_e32 v[24:25], 0
	v_mov_b64_e32 v[26:27], 0
	v_mov_b64_e32 v[28:29], 0
	v_mov_b64_e32 v[30:31], 0
	v_mov_b64_e32 v[32:33], 0
	v_mov_b64_e32 v[34:35], 0
	v_mov_b64_e32 v[36:37], 0
	v_mov_b64_e32 v[38:39], 0
	v_mov_b64_e32 v[40:41], 0
	v_mov_b64_e32 v[42:43], 0
	v_mov_b64_e32 v[44:45], 0
	v_mov_b64_e32 v[46:47], 0
	v_mov_b64_e32 v[48:49], 0
	v_mov_b64_e32 v[50:51], 0
	v_mov_b64_e32 v[52:53], 0
	v_mov_b64_e32 v[54:55], 0
	v_mov_b64_e32 v[56:57], 0
	v_mov_b64_e32 v[58:59], 0
	v_mov_b64_e32 v[60:61], 0
	v_mov_b64_e32 v[62:63], 0
	v_mov_b64_e32 v[64:65], 0
	v_mov_b64_e32 v[66:67], 0
	v_mov_b64_e32 v[68:69], 0
	v_mov_b64_e32 v[70:71], 0
	v_mov_b64_e32 v[72:73], 0
	v_mov_b64_e32 v[74:75], 0
	v_mov_b64_e32 v[76:77], 0
	v_mov_b64_e32 v[78:79], 0
	v_mov_b64_e32 v[80:81], 0
	v_mov_b64_e32 v[82:83], 0
	v_mov_b64_e32 v[84:85], 0
	v_mov_b64_e32 v[86:87], 0
	v_mov_b64_e32 v[88:89], 0
	v_mov_b64_e32 v[90:91], 0
	v_mov_b64_e32 v[92:93], 0
	v_mov_b64_e32 v[94:95], 0
	v_mov_b64_e32 v[96:97], 0
	v_mov_b64_e32 v[98:99], 0
	v_mov_b64_e32 v[100:101], 0
	v_mov_b64_e32 v[102:103], 0
	v_mov_b64_e32 v[104:105], 0
	v_mov_b64_e32 v[106:107], 0
	v_mov_b64_e32 v[108:109], 0
	v_mov_b64_e32 v[110:111], 0
	v_mov_b64_e32 v[112:113], 0
	v_mov_b64_e32 v[114:115], 0
	v_mov_b64_e32 v[116:117], 0
	v_mov_b64_e32 v[118:119], 0
	v_mov_b64_e32 v[120:121], 0
	v_mov_b64_e32 v[122:123], 0
	v_mov_b64_e32 v[124:125], 0
	v_mov_b64_e32 v[126:127], 0
	v_mov_b64_e32 v[128:129], 0

.LBB0_330:
	s_add_u32 s40, s22, 0x100
	s_addc_u32 s41, s23, 0
	s_mov_b32 s51, -2
	v_mov_b64_e32 v[2:3], 0
	v_mov_b64_e32 v[4:5], 0
	v_mov_b64_e32 v[6:7], 0
	v_mov_b64_e32 v[8:9], 0
	v_mov_b64_e32 v[10:11], 0
	v_mov_b64_e32 v[12:13], 0
	v_mov_b64_e32 v[14:15], 0
	v_mov_b64_e32 v[16:17], 0
	v_mov_b64_e32 v[18:19], 0
	v_mov_b64_e32 v[20:21], 0
	v_mov_b64_e32 v[22:23], 0
	v_mov_b64_e32 v[24:25], 0
	v_mov_b64_e32 v[26:27], 0
	v_mov_b64_e32 v[28:29], 0
	v_mov_b64_e32 v[30:31], 0
	v_mov_b64_e32 v[32:33], 0
	v_mov_b64_e32 v[34:35], 0
	v_mov_b64_e32 v[36:37], 0
	v_mov_b64_e32 v[38:39], 0
	v_mov_b64_e32 v[40:41], 0
	v_mov_b64_e32 v[42:43], 0
	v_mov_b64_e32 v[44:45], 0
	v_mov_b64_e32 v[46:47], 0
	v_mov_b64_e32 v[48:49], 0
	v_mov_b64_e32 v[50:51], 0
	v_mov_b64_e32 v[52:53], 0
	v_mov_b64_e32 v[54:55], 0
	v_mov_b64_e32 v[56:57], 0
	v_mov_b64_e32 v[58:59], 0
	v_mov_b64_e32 v[60:61], 0
	v_mov_b64_e32 v[62:63], 0
	v_mov_b64_e32 v[64:65], 0
	v_mov_b64_e32 v[66:67], 0
	v_mov_b64_e32 v[68:69], 0
	v_mov_b64_e32 v[70:71], 0
	v_mov_b64_e32 v[72:73], 0
	v_mov_b64_e32 v[74:75], 0
	v_mov_b64_e32 v[76:77], 0
	v_mov_b64_e32 v[78:79], 0
	v_mov_b64_e32 v[80:81], 0
	v_mov_b64_e32 v[82:83], 0
	v_mov_b64_e32 v[84:85], 0
	v_mov_b64_e32 v[86:87], 0
	v_mov_b64_e32 v[88:89], 0
	v_mov_b64_e32 v[90:91], 0
	v_mov_b64_e32 v[92:93], 0
	v_mov_b64_e32 v[94:95], 0
	v_mov_b64_e32 v[96:97], 0
	v_mov_b64_e32 v[98:99], 0
	v_mov_b64_e32 v[100:101], 0
	v_mov_b64_e32 v[102:103], 0
	v_mov_b64_e32 v[104:105], 0
	v_mov_b64_e32 v[106:107], 0
	v_mov_b64_e32 v[108:109], 0
	v_mov_b64_e32 v[110:111], 0
	v_mov_b64_e32 v[112:113], 0
	v_mov_b64_e32 v[114:115], 0
	v_mov_b64_e32 v[116:117], 0
	v_mov_b64_e32 v[118:119], 0
	v_mov_b64_e32 v[120:121], 0
	v_mov_b64_e32 v[122:123], 0
	v_mov_b64_e32 v[124:125], 0
	v_mov_b64_e32 v[126:127], 0
	v_mov_b64_e32 v[128:129], 0

.LBB0_359:
	s_ashr_i32 s35, s34, 31
	v_cmp_lt_i64_e32 vcc, s[36:37], v[156:157]
	s_lshl_b64 s[36:37], s[34:35], 19
	s_add_u32 s36, s12, s36
	s_addc_u32 s37, s13, s37
	s_and_b64 s[40:41], vcc, exec
	s_cselect_b32 s1, s37, s45
	s_cselect_b32 s3, s36, s44
	s_ashr_i32 s31, s30, 31
	s_lshl_b64 s[40:41], s[30:31], 19
	s_add_u32 s40, s48, s40
	s_addc_u32 s41, s49, s41
	s_and_b64 s[46:47], vcc, exec
	s_cselect_b32 s31, s41, s43
	s_cselect_b32 s35, s40, s42
	s_add_u32 s60, s42, 0x100
	s_addc_u32 s61, s43, 0
	s_add_u32 s42, s44, 0x40080
	s_addc_u32 s43, s45, 0
	s_mov_b32 s62, -2
	v_mov_b64_e32 v[2:3], 0
	v_mov_b64_e32 v[4:5], 0
	v_mov_b64_e32 v[6:7], 0
	v_mov_b64_e32 v[8:9], 0
	v_mov_b64_e32 v[10:11], 0
	v_mov_b64_e32 v[12:13], 0
	v_mov_b64_e32 v[14:15], 0
	v_mov_b64_e32 v[16:17], 0
	v_mov_b64_e32 v[18:19], 0
	v_mov_b64_e32 v[20:21], 0
	v_mov_b64_e32 v[22:23], 0
	v_mov_b64_e32 v[24:25], 0
	v_mov_b64_e32 v[26:27], 0
	v_mov_b64_e32 v[28:29], 0
	v_mov_b64_e32 v[30:31], 0
	v_mov_b64_e32 v[32:33], 0
	v_mov_b64_e32 v[34:35], 0
	v_mov_b64_e32 v[36:37], 0
	v_mov_b64_e32 v[38:39], 0
	v_mov_b64_e32 v[40:41], 0
	v_mov_b64_e32 v[42:43], 0
	v_mov_b64_e32 v[44:45], 0
	v_mov_b64_e32 v[46:47], 0
	v_mov_b64_e32 v[48:49], 0
	v_mov_b64_e32 v[50:51], 0
	v_mov_b64_e32 v[52:53], 0
	v_mov_b64_e32 v[54:55], 0
	v_mov_b64_e32 v[56:57], 0
	v_mov_b64_e32 v[58:59], 0
	v_mov_b64_e32 v[60:61], 0
	v_mov_b64_e32 v[62:63], 0
	v_mov_b64_e32 v[64:65], 0
	v_mov_b64_e32 v[66:67], 0
	v_mov_b64_e32 v[68:69], 0
	v_mov_b64_e32 v[70:71], 0
	v_mov_b64_e32 v[72:73], 0
	v_mov_b64_e32 v[74:75], 0
	v_mov_b64_e32 v[76:77], 0
	v_mov_b64_e32 v[78:79], 0
	v_mov_b64_e32 v[80:81], 0
	v_mov_b64_e32 v[98:99], 0
	v_mov_b64_e32 v[100:101], 0
	v_mov_b64_e32 v[102:103], 0
	v_mov_b64_e32 v[104:105], 0
	v_mov_b64_e32 v[106:107], 0
	v_mov_b64_e32 v[108:109], 0
	v_mov_b64_e32 v[110:111], 0
	v_mov_b64_e32 v[112:113], 0
	v_mov_b64_e32 v[114:115], 0
	v_mov_b64_e32 v[116:117], 0
	v_mov_b64_e32 v[118:119], 0
	v_mov_b64_e32 v[120:121], 0
	v_mov_b64_e32 v[122:123], 0
	v_mov_b64_e32 v[124:125], 0
	v_mov_b64_e32 v[126:127], 0
	v_mov_b64_e32 v[128:129], 0
	v_mov_b64_e32 v[130:131], 0
	v_mov_b64_e32 v[132:133], 0
	v_mov_b64_e32 v[134:135], 0
	v_mov_b64_e32 v[136:137], 0
	v_mov_b64_e32 v[138:139], 0
	v_mov_b64_e32 v[140:141], 0
	v_mov_b64_e32 v[142:143], 0
	v_mov_b64_e32 v[144:145], 0

.LBB0_585:
	s_ashr_i32 s9, s8, 31
	v_cmp_lt_i64_e32 vcc, s[16:17], v[160:161]
	s_lshl_b64 s[16:17], s[8:9], 19
	s_add_u32 s16, s12, s16
	s_addc_u32 s17, s13, s17
	s_and_b64 s[18:19], vcc, exec
	s_cselect_b32 s9, s17, s21
	s_cselect_b32 s43, s16, s20
	s_ashr_i32 s1, s0, 31
	s_lshl_b64 s[18:19], s[0:1], 19
	s_add_u32 s18, s27, s18
	s_addc_u32 s19, s28, s19
	s_and_b64 s[24:25], vcc, exec
	s_cselect_b32 s1, s19, s23
	s_cselect_b32 s44, s18, s22
	s_add_u32 s20, s20, 0x40080
	s_addc_u32 s21, s21, 0
	s_add_u32 s45, s22, 0x100
	s_addc_u32 s46, s23, 0
	s_mov_b32 s47, -2
	v_mov_b64_e32 v[2:3], 0
	v_mov_b64_e32 v[4:5], 0
	v_mov_b64_e32 v[6:7], 0
	v_mov_b64_e32 v[8:9], 0
	v_mov_b64_e32 v[10:11], 0
	v_mov_b64_e32 v[12:13], 0
	v_mov_b64_e32 v[14:15], 0
	v_mov_b64_e32 v[16:17], 0
	v_mov_b64_e32 v[18:19], 0
	v_mov_b64_e32 v[20:21], 0
	v_mov_b64_e32 v[22:23], 0
	v_mov_b64_e32 v[24:25], 0
	v_mov_b64_e32 v[26:27], 0
	v_mov_b64_e32 v[28:29], 0
	v_mov_b64_e32 v[30:31], 0
	v_mov_b64_e32 v[32:33], 0
	v_mov_b64_e32 v[34:35], 0
	v_mov_b64_e32 v[36:37], 0
	v_mov_b64_e32 v[38:39], 0
	v_mov_b64_e32 v[40:41], 0
	v_mov_b64_e32 v[42:43], 0
	v_mov_b64_e32 v[44:45], 0
	v_mov_b64_e32 v[46:47], 0
	v_mov_b64_e32 v[48:49], 0
	v_mov_b64_e32 v[50:51], 0
	v_mov_b64_e32 v[52:53], 0
	v_mov_b64_e32 v[54:55], 0
	v_mov_b64_e32 v[56:57], 0
	v_mov_b64_e32 v[58:59], 0
	v_mov_b64_e32 v[60:61], 0
	v_mov_b64_e32 v[62:63], 0
	v_mov_b64_e32 v[64:65], 0
	v_mov_b64_e32 v[66:67], 0
	v_mov_b64_e32 v[68:69], 0
	v_mov_b64_e32 v[70:71], 0
	v_mov_b64_e32 v[72:73], 0
	v_mov_b64_e32 v[74:75], 0
	v_mov_b64_e32 v[76:77], 0
	v_mov_b64_e32 v[78:79], 0
	v_mov_b64_e32 v[80:81], 0
	v_mov_b64_e32 v[82:83], 0
	v_mov_b64_e32 v[84:85], 0
	v_mov_b64_e32 v[86:87], 0
	v_mov_b64_e32 v[88:89], 0
	v_mov_b64_e32 v[90:91], 0
	v_mov_b64_e32 v[92:93], 0
	v_mov_b64_e32 v[94:95], 0
	v_mov_b64_e32 v[96:97], 0
	v_mov_b64_e32 v[98:99], 0
	v_mov_b64_e32 v[100:101], 0
	v_mov_b64_e32 v[102:103], 0
	v_mov_b64_e32 v[104:105], 0
	v_mov_b64_e32 v[106:107], 0
	v_mov_b64_e32 v[108:109], 0
	v_mov_b64_e32 v[110:111], 0
	v_mov_b64_e32 v[112:113], 0
	v_mov_b64_e32 v[114:115], 0
	v_mov_b64_e32 v[116:117], 0
	v_mov_b64_e32 v[118:119], 0
	v_mov_b64_e32 v[120:121], 0
	v_mov_b64_e32 v[122:123], 0
	v_mov_b64_e32 v[124:125], 0
	v_mov_b64_e32 v[126:127], 0
	v_mov_b64_e32 v[128:129], 0
